# layer-1 mixer work placement: SWA sub-grid index = vb mod 384, so the 2-item SWA blocks are the ones sharing a CU with the GLA chain blocks
# baseline (speedup 1.0000x reference)
; __global__ void __launch_bounds__(NTHR, 2) mega(P p) {
;     ...
;       const bool split0 = subgrid;
;       const int svb = split0 ? vb - 256 : vb, snvb = split0 ? nvb - 256 : nvb;
;       if (!split0 || vb < 256)
;         for (int cid = vb; cid < 256; cid += (split0 ? 256 : nvb)) gdn_chain(p, cid, smem);
;       __syncthreads();
;       if (!split0 || vb >= 256) {
;         XcdBarrier& bs = split0 ? xb2 : xb;
;         {
;           GemmDesc g = gemm_simple((const u16*)(ws + OFF_REGB), EVEN_IN, (const u16*)(ws + OFF_WQUP), 384, T, 768);
;           g.o16 = (u16*)(ws + OFF_QB); g.ldo = 768; g.nreal = 768;
;           gemm_auto<EPI_STORE>(g, T, smem, svb, snvb);
;     ...
;       const bool split1 = nvb >= 256;
;       if (!split1 || vb < 128)
;         for (int cid = vb; cid < 128; cid += (split1 ? 128 : nvb)) gla_chain_mfma(p, cid, smem);
;       __syncthreads();
;       if (!split1 || vb >= 128)
;       {
;         const u16* Q = (const u16*)(ws + OFF_QB);
;         const u16* Kb = (const u16*)(ws + OFF_KB);
;         const u16* z = (const u16*)(ws + OFF_REGB);
;         for (int it = (split1 ? vb - 128 : vb); it < 1024; it += (split1 ? nvb - 128 : nvb)) {
.LBB0_127:
	s_or_b64 exec, exec, s[4:5]
	s_load_dwordx16 s[16:31], s[0:1], 0x80
	s_add_i32 s3, s92, 0xffffff00
	s_add_i32 s4, s2, 0xffffff00
	s_mov_b32 s43, s92
	v_lshl_add_u64 v[0:1], v[0:1], 2, s[72:73]
	s_waitcnt lgkmcnt(0)
	v_writelane_b32 v223, s16, 38
	v_mbcnt_lo_u32_b32 v135, -1, 0
	v_mbcnt_hi_u32_b32 v136, -1, v135
	v_writelane_b32 v223, s17, 39
	v_writelane_b32 v223, s18, 40
	v_writelane_b32 v223, s19, 41
	v_writelane_b32 v223, s20, 42
	v_writelane_b32 v223, s21, 43
	v_writelane_b32 v223, s22, 44
	v_writelane_b32 v223, s23, 45
	v_writelane_b32 v223, s24, 46
	v_writelane_b32 v223, s25, 47
	v_writelane_b32 v223, s26, 48
	v_writelane_b32 v223, s27, 49
	v_writelane_b32 v223, s28, 50
	v_writelane_b32 v223, s29, 51
	v_writelane_b32 v223, s30, 52
	v_writelane_b32 v223, s31, 53
	v_and_b32_e32 v138, 64, v136
	v_readlane_b32 s14, v223, 4
	v_readlane_b32 s15, v223, 5
	s_and_b64 s[0:1], s[14:15], exec
	s_cselect_b32 s24, s4, s2
	s_cselect_b32 s25, s3, s92
	s_and_b32 s0, s25, 7
	s_and_b32 s1, s24, 7
	s_cmp_eq_u32 s0, 0
	s_mul_i32 s1, s1, 12
	s_cselect_b32 s4, s1, 0
	s_ashr_i32 s1, s25, 3
	s_cmp_eq_u32 s0, 0
	s_cselect_b32 s26, s1, s25
	s_ashr_i32 s1, s24, 3
	s_cmp_eq_u32 s0, 0
	s_cselect_b32 s6, 12, 0x60
	s_cselect_b32 s27, s1, s24
	s_and_b32 s3, s92, 7
	s_and_b32 s7, s2, 7
	s_cmpk_lt_i32 s92, 0x100
	s_cselect_b64 s[0:1], -1, 0
	s_and_b64 s[0:1], s[0:1], exec
	s_cselect_b32 s0, s92, 0x80
	s_lshl_b32 s5, s7, 4
	s_cmp_eq_u32 s3, 0
	v_writelane_b32 v223, s0, 54
	s_cselect_b64 s[0:1], -1, 0
	v_writelane_b32 v223, s7, 55
	s_mul_i32 s7, s7, 12
	s_and_b64 s[0:1], s[0:1], exec
	s_cselect_b32 s54, s7, 0
	s_cselect_b32 s7, 16, 0x80
	s_cselect_b32 s0, s5, 0
	s_ashr_i32 s5, s92, 3
	s_cmp_eq_u32 s3, 0
	v_writelane_b32 v223, s0, 56
	s_cselect_b64 s[0:1], -1, 0
	s_and_b64 s[0:1], s[0:1], exec
	s_cselect_b32 s28, s5, s92
	s_ashr_i32 s5, s2, 3
	s_cmp_eq_u32 s3, 0
	s_cselect_b64 s[0:1], -1, 0
	v_writelane_b32 v223, s0, 57
	v_mov_b32_e32 v96, 0
	v_mov_b32_e32 v117, 0
	v_writelane_b32 v223, s1, 58
	s_and_b64 s[0:1], s[0:1], exec
	s_cselect_b32 s16, 12, 0x60
	s_cselect_b32 s29, s5, s2
	s_add_i32 s3, s92, 0xffffff80
	s_cmpk_lt_i32 s92, 0x100
	s_cselect_b64 s[0:1], -1, 0
	s_and_b64 s[0:1], s[0:1], exec
	s_cselect_b32 s30, s92, s3
	s_add_i32 s3, s2, 0xfffffe80
	s_cmpk_lt_i32 s2, 0x180
	s_cselect_b32 s3, s2, s3
	s_cmpk_lt_i32 s92, 0x100
	s_cselect_b64 s[0:1], -1, 0
	s_and_b64 s[8:9], s[0:1], exec
	s_cselect_b32 s31, s2, s3
	s_add_u32 s3, s70, 0x2a32000
	s_addc_u32 s33, s71, 0
	s_lshl_b32 s34, s92, 2
	s_add_i32 s5, s34, 0x47ff
	s_lshl_b32 s38, s2, 2
	s_add_u32 s8, s70, 0x3472000
	s_addc_u32 s9, s71, 0
	v_writelane_b32 v223, s8, 59
	v_mov_b32_e32 v119, 0x358637bd
	v_mov_b32_e32 v133, 1
	v_writelane_b32 v223, s9, 60
	s_add_u32 s8, s70, 0x2990000
	v_writelane_b32 v223, s8, 61
	s_addc_u32 s8, s71, 0
	v_writelane_b32 v223, s8, 62
	s_add_u32 s8, s70, 0x11572200
	s_addc_u32 s9, s71, 0
	v_writelane_b32 v223, s8, 63
	v_mov_b32_e32 v134, 0x3ecc95a3
	v_xor_b32_e32 v137, 32, v136
	v_writelane_b32 v222, s9, 0
	s_add_u32 s8, s70, 0x11572400
	s_addc_u32 s9, s71, 0
	v_writelane_b32 v222, s8, 1
	v_add_u32_e32 v139, 64, v138
	v_xor_b32_e32 v140, 16, v136
	v_writelane_b32 v222, s9, 2
	s_add_u32 s8, s70, 0x11572500
	s_addc_u32 s9, s71, 0
	v_writelane_b32 v222, s8, 3
	v_xor_b32_e32 v141, 8, v136
	v_xor_b32_e32 v142, 4, v136
	v_writelane_b32 v222, s9, 4
	s_add_u32 s8, s70, 0x11572600
	s_addc_u32 s9, s71, 0
	v_writelane_b32 v222, s8, 5
	v_xor_b32_e32 v143, 2, v136
	v_xor_b32_e32 v144, 1, v136
	v_writelane_b32 v222, s9, 6
	s_add_u32 s8, s70, 0x11572700
	s_addc_u32 s9, s71, 0
	v_writelane_b32 v222, s8, 7
	v_mov_b32_e32 v145, 0x42800000
	v_not_b32_e32 v146, 63
	v_writelane_b32 v222, s9, 8
	s_add_u32 s8, s70, 0x11572800
	s_addc_u32 s9, s71, 0
	v_writelane_b32 v222, s8, 9
	v_mov_b32_e32 v147, 0x41b17218
	v_mov_b32_e32 v148, 0x80
	v_writelane_b32 v222, s9, 10
	s_add_u32 s8, s70, 0x11572900
	s_addc_u32 s9, s71, 0
	v_writelane_b32 v222, s8, 11
	v_mov_b32_e32 v149, 0xff800000
	v_mov_b32_e32 v114, 0x3f317218
	v_writelane_b32 v222, s9, 12
	s_add_u32 s8, s70, 0x11572a00
	s_addc_u32 s9, s71, 0
	v_writelane_b32 v222, s8, 13
	v_mov_b32_e32 v150, 0x7f800000
	v_mov_b32_e32 v151, 0x7fc00000
	v_writelane_b32 v222, s9, 14
	s_add_u32 s8, s70, 0x11572b00
	s_addc_u32 s9, s71, 0
	v_writelane_b32 v222, s8, 15
	v_mov_b32_e32 v152, 0
	s_movk_i32 s48, 0x47ff
	v_writelane_b32 v222, s9, 16
	s_add_u32 s8, s70, 0x11572c00
	s_addc_u32 s9, s71, 0
	v_writelane_b32 v222, s8, 17
	s_movk_i32 s49, 0x600
	s_mov_b64 s[96:97], 0x3472080
	v_writelane_b32 v222, s9, 18
	s_add_u32 s8, s70, 0x11572d00
	s_addc_u32 s9, s71, 0
	v_writelane_b32 v222, s8, 19
	s_mov_b64 s[50:51], 0x3482080
	s_nop 0
	v_writelane_b32 v222, s9, 20
	s_add_u32 s8, s70, 0x11572e00
	s_addc_u32 s9, s71, 0
	v_writelane_b32 v222, s8, 21
	s_barrier
; DI unsigned xb_ld(unsigned* p) { return __hip_atomic_load(p, __ATOMIC_RELAXED, __HIP_MEMORY_SCOPE_AGENT); }
; template <int EPI, int MI>
; DI void gemm_phase(const GemmDesc& g, char* smem, int vb, int nvb) {
;   const bool xm = (nvb & 7) == 0 && (g.nM & 7) == 0;
;   const int xcd = vb & 7;
;   const int mPer = xm ? (g.nM >> 3) : g.nM;
;   const int PM = (mPer % 9 == 0) ? 9 : ((mPer & 7) == 0 ? 8 : ((mPer % 6) == 0 ? 6 : mPer));
;   const int per = PM * g.nN;
;   const int local = mPer * g.nN;
;   const int start = xm ? (vb >> 3) : vb, step = xm ? (nvb >> 3) : nvb;
;   const int mbase = xm ? xcd * mPer : 0;
; DI void xcd_barrier_complete(unsigned* bar, unsigned x, unsigned G, unsigned& nloc, unsigned& nx) {
;   unsigned sum, cnt, mine, sp = 0u;
;   for (;;) {
;     sum = 0u; cnt = 0u; mine = 0u;
; #pragma unroll
;     for (unsigned j = 0; j < 16; ++j) { const unsigned c = xb_ld(&bar[XB_XCNT(j)]); sum += c; cnt += (c > 0u) ? 1u : 0u; mine = (j == x) ? c : mine; }
;     if (sum == G) break;
;     __builtin_amdgcn_s_sleep(1);
;     if ((++sp & 255u) == 0u) { if (xb_ld(&bar[XB_TMO])) break; if (sp > XB_SPIN_CAP) { atomicAdd(&bar[XB_TMO], 1u); break; } }
;   }
;   nloc = mine > 0u ? mine : 1u; nx = cnt > 0u ? cnt : 1u;
	s_nop 0
	v_writelane_b32 v222, s9, 22
	s_add_u32 s8, s70, 0x11572f00
	s_addc_u32 s9, s71, 0
	v_writelane_b32 v222, s8, 23
	s_nop 1
	v_writelane_b32 v222, s9, 24
	s_add_u32 s8, s70, 0x11573000
	s_addc_u32 s9, s71, 0
	v_writelane_b32 v222, s8, 25
	s_nop 1
	v_writelane_b32 v222, s9, 26
	s_add_u32 s8, s70, 0x11573100
	s_addc_u32 s9, s71, 0
	v_writelane_b32 v222, s8, 27
	s_nop 1
	v_writelane_b32 v222, s9, 28
	s_add_u32 s8, s70, 0x11573200
	s_addc_u32 s9, s71, 0
	v_writelane_b32 v222, s8, 29
	s_nop 1
	v_writelane_b32 v222, s9, 30
	s_add_u32 s8, s70, 0x11573300
	s_addc_u32 s9, s71, 0
	v_writelane_b32 v222, s8, 31
	s_cmp_eq_u32 s74, 15
	s_nop 0
	v_writelane_b32 v222, s9, 32
	s_cselect_b64 s[8:9], -1, 0
	v_writelane_b32 v222, s8, 33
	s_cmp_eq_u32 s74, 14
	s_nop 0
	v_writelane_b32 v222, s9, 34
	s_cselect_b64 s[8:9], -1, 0
	v_writelane_b32 v222, s8, 35
	s_cmp_eq_u32 s74, 13
	s_nop 0
	v_writelane_b32 v222, s9, 36
	s_cselect_b64 s[8:9], -1, 0
	v_writelane_b32 v222, s8, 37
	s_cmp_eq_u32 s74, 12
	s_nop 0
	v_writelane_b32 v222, s9, 38
	s_cselect_b64 s[8:9], -1, 0
	v_writelane_b32 v222, s8, 39
	s_cmp_eq_u32 s74, 11
	s_nop 0
	v_writelane_b32 v222, s9, 40
	s_cselect_b64 s[8:9], -1, 0
	v_writelane_b32 v222, s8, 41
	s_cmp_eq_u32 s74, 10
	s_nop 0
	v_writelane_b32 v222, s9, 42
	s_cselect_b64 s[8:9], -1, 0
	v_writelane_b32 v222, s8, 43
	s_cmp_eq_u32 s74, 9
	s_nop 0
	v_writelane_b32 v222, s9, 44
	s_cselect_b64 s[8:9], -1, 0
	v_writelane_b32 v222, s8, 45
	s_cmp_eq_u32 s74, 8
	s_nop 0
	v_writelane_b32 v222, s9, 46
	s_cselect_b64 s[8:9], -1, 0
	v_writelane_b32 v222, s8, 47
	s_cmp_eq_u32 s74, 7
	s_nop 0
	v_writelane_b32 v222, s9, 48
	s_cselect_b64 s[8:9], -1, 0
	v_writelane_b32 v222, s8, 49
	s_cmp_eq_u32 s74, 6
	s_nop 0
	v_writelane_b32 v222, s9, 50
	s_cselect_b64 s[8:9], -1, 0
	v_writelane_b32 v222, s8, 51
	s_cmp_eq_u32 s74, 5
	s_nop 0
	v_writelane_b32 v222, s9, 52
	s_cselect_b64 s[8:9], -1, 0
	v_writelane_b32 v222, s8, 53
	s_cmp_eq_u32 s74, 4
	s_nop 0
	v_writelane_b32 v222, s9, 54
	s_cselect_b64 s[8:9], -1, 0
	v_writelane_b32 v222, s8, 55
	s_cmp_eq_u32 s74, 3
	s_nop 0
	v_writelane_b32 v222, s9, 56
	s_cselect_b64 s[8:9], -1, 0
	v_writelane_b32 v222, s8, 57
	s_cmp_eq_u32 s74, 2
	s_nop 0
	v_writelane_b32 v222, s9, 58
	s_cselect_b64 s[8:9], -1, 0
	v_writelane_b32 v222, s8, 59
	s_cmp_eq_u32 s74, 1
	s_nop 0
	v_writelane_b32 v222, s9, 60
	s_cselect_b64 s[8:9], -1, 0
	v_writelane_b32 v222, s8, 61
	s_cmp_eq_u32 s74, 0
	s_nop 0
	v_writelane_b32 v222, s9, 62
	s_cselect_b64 s[8:9], -1, 0
	v_writelane_b32 v222, s8, 63
	s_nop 1
	v_writelane_b32 v221, s9, 0
	s_add_u32 s8, s70, 0x11575400
	s_addc_u32 s9, s71, 0
	v_writelane_b32 v221, s8, 1
	s_nop 1
	v_writelane_b32 v221, s9, 2
	s_add_u32 s8, s70, 0x11575500
	s_addc_u32 s9, s71, 0
	v_writelane_b32 v221, s8, 3
	s_nop 1
	v_writelane_b32 v221, s9, 4
	s_add_u32 s8, s70, 0x5872000
	s_addc_u32 s9, s71, 0
	v_writelane_b32 v221, s8, 5
	s_bitcmp0_b32 s16, 2
	s_nop 0
	v_writelane_b32 v221, s9, 6
	s_mul_i32 s8, s16, 57
	s_cselect_b32 s9, 8, 6
	s_and_b32 s8, s8, 0xfc
	s_cmp_gt_u32 s8, 28
	s_mul_i32 s8, s16, 44
	s_cselect_b32 s40, s9, 9
	s_cmp_lt_i32 s29, s8
	v_writelane_b32 v221, s8, 7
	s_cselect_b64 s[8:9], -1, 0
	v_writelane_b32 v221, s8, 8
	s_nop 1
	v_writelane_b32 v221, s9, 9
	s_add_u32 s8, s70, 0x1600000
	s_addc_u32 s9, s71, 0
	v_writelane_b32 v221, s8, 10
	s_lshl_b32 s35, s40, 3
	s_nop 0
	v_writelane_b32 v221, s9, 11
	s_lshl_b32 s8, s16, 3
	v_writelane_b32 v221, s16, 12
	s_cmp_lt_i32 s29, s8
	v_writelane_b32 v221, s8, 13
	s_cselect_b64 s[8:9], -1, 0
	v_writelane_b32 v221, s8, 14
	s_nop 1
	v_writelane_b32 v221, s9, 15
	s_add_u32 s8, s70, 0x2100000
	s_addc_u32 s9, s71, 0
	s_add_u32 s36, s70, 0x3232000
	v_writelane_b32 v221, s8, 16
	s_addc_u32 s37, s71, 0
	s_nop 0
	v_writelane_b32 v221, s9, 17
	s_add_u32 s8, s70, 0xbb72000
	s_addc_u32 s9, s71, 0
	v_writelane_b32 v221, s8, 18
	s_nop 1
	v_writelane_b32 v221, s9, 19
	s_add_u32 s8, s70, 0xd672000
	v_writelane_b32 v221, s8, 20
	s_addc_u32 s8, s71, 0
	s_cmpk_lt_i32 s2, 0x80
	v_writelane_b32 v221, s8, 21
	s_cselect_b64 s[8:9], -1, 0
	v_writelane_b32 v221, s8, 22
	s_cmpk_gt_i32 s2, 0x7f
	s_nop 0
	v_writelane_b32 v221, s9, 23
	s_cselect_b64 s[8:9], -1, 0
	s_add_u32 s92, s70, 0xf172000
	v_writelane_b32 v221, s2, 24
	s_addc_u32 s93, s71, 0
	s_or_b64 s[0:1], s[8:9], s[0:1]
	v_writelane_b32 v221, s0, 25
	s_cmpk_lt_i32 s31, 0x400
	s_nop 0
	v_writelane_b32 v221, s1, 26
	s_cselect_b64 s[0:1], -1, 0
	v_writelane_b32 v221, s0, 27
	s_cmpk_lt_i32 s31, 0x940
	s_nop 0
	v_writelane_b32 v221, s1, 28
	s_cselect_b64 s[0:1], -1, 0
	v_writelane_b32 v221, s0, 29
	s_nop 1
	v_writelane_b32 v221, s1, 30
	s_add_u32 s0, s70, 0x2790000
	s_addc_u32 s1, s71, 0
	v_writelane_b32 v221, s0, 31
	s_nop 1
	v_writelane_b32 v221, s1, 32
	s_add_u32 s0, s70, 0x29e1000
	v_writelane_b32 v221, s0, 33
	s_addc_u32 s0, s71, 0
	v_writelane_b32 v221, s0, 34
	s_mul_i32 s0, s7, 57
	s_and_b32 s0, s0, 0xf0
	s_cmp_lt_u32 s0, 29
	s_cselect_b32 s39, 9, 8
	s_lshl_b32 s0, s7, 3
	s_lshl_b32 s7, s39, 3
	s_cmp_lt_i32 s29, s0
	v_writelane_b32 v221, s0, 35
	s_cselect_b64 s[0:1], -1, 0
	v_writelane_b32 v221, s0, 36
	s_nop 1
	v_writelane_b32 v221, s1, 37
	s_xor_b64 s[0:1], s[14:15], -1
	s_and_b64 s[8:9], s[14:15], exec
	s_cselect_b32 s2, 0x100, s43
	v_writelane_b32 v221, s2, 38
	s_or_b64 s[0:1], s[12:13], s[0:1]
	v_writelane_b32 v221, s0, 39
	s_nop 1
	v_writelane_b32 v221, s1, 40
	s_add_u32 s0, s70, 0x2680000
	s_addc_u32 s1, s71, 0
	v_writelane_b32 v221, s0, 41
	s_bitcmp0_b32 s6, 2
	s_nop 0
	v_writelane_b32 v221, s1, 42
	s_mul_i32 s0, s6, 57
	s_cselect_b32 s1, 8, 6
	s_and_b32 s0, s0, 0xfc
	s_cmp_gt_u32 s0, 28
	s_mul_i32 s0, s6, 6
	s_cselect_b32 s41, s1, 9
; DI unsigned xb_ld(unsigned* p) { return __hip_atomic_load(p, __ATOMIC_RELAXED, __HIP_MEMORY_SCOPE_AGENT); }
; DI unsigned xb_add(unsigned* p, unsigned v) { return __hip_atomic_fetch_add(p, v, __ATOMIC_RELAXED, __HIP_MEMORY_SCOPE_AGENT); }
; #define XB_SPIN(cond, bar) do { unsigned _sp = 0; while (cond) { __builtin_amdgcn_s_sleep(1); \
;     if ((++_sp & 255u) == 0u) { if (xb_ld(&(bar)[XB_TMO])) break; if (_sp > XB_SPIN_CAP) { atomicAdd(&(bar)[XB_TMO], 1u); break; } } } } while (0)
; DI void xcd_barrier(XcdBarrier& b) {
;   asm volatile("s_waitcnt vmcnt(0)" ::: "memory");
;   __syncthreads();
;   if (threadIdx.x == 0) {
;     unsigned* bar = b.bar;
;     __builtin_amdgcn_s_waitcnt(0);
;     unsigned nloc = b.nloc, nx = b.nx;
;     if (nloc == 0u) { xcd_barrier_complete(bar, b.x, b.G, nloc, nx); b.nloc = nloc; b.nx = nx; }
;     const unsigned old = xb_add(&bar[XB_XSUB(b.x)], 1u);
;     const unsigned gen = old / nloc;
;     if (old + 1u == (gen + 1u) * nloc) {
;       __builtin_amdgcn_fence(__ATOMIC_RELEASE, "agent");
;       asm volatile("s_waitcnt vmcnt(0)" ::: "memory");
;       const unsigned og = xb_add(&bar[XB_TOP], 1u);
;       const unsigned tg = og / nx;
;       if (og + 1u == (tg + 1u) * nx) xb_add(&bar[XB_TOPGEN], 1u);
;       else XB_SPIN(xb_ld(&bar[XB_TOPGEN]) == tg, bar);
;       __builtin_amdgcn_fence(__ATOMIC_ACQUIRE, "agent");
;       xb_add(&bar[XB_XGEN(b.x)], 1u);
;       asm volatile("s_waitcnt vmcnt(0)" ::: "memory");
;     } else {
;       XB_SPIN(xb_ld(&bar[XB_XGEN(b.x)]) == gen, bar);
;       __builtin_amdgcn_fence(__ATOMIC_ACQUIRE, "agent");
;       asm volatile("s_waitcnt vmcnt(0)" ::: "memory");
;     }
; __global__ void __launch_bounds__(NTHR, 2) mega(P p) {
;     ...
;     if (layer == 0) {
;       const bool split0 = subgrid;
;       const int svb = split0 ? vb - 256 : vb, snvb = split0 ? nvb - 256 : nvb;
;       if (!split0 || vb < 256)
;         for (int cid = vb; cid < 256; cid += (split0 ? 256 : nvb)) gdn_chain(p, cid, smem);
;       __syncthreads();
;       if (!split0 || vb >= 256) {
;         XcdBarrier& bs = split0 ? xb2 : xb;
	s_cmp_lt_i32 s27, s0
	v_writelane_b32 v221, s0, 43
	s_cselect_b64 s[0:1], -1, 0
	v_writelane_b32 v221, s0, 44
	s_nop 1
	v_writelane_b32 v221, s1, 45
	s_add_u32 s0, s70, 0x5872300
	s_addc_u32 s1, s71, 0
	v_writelane_b32 v221, s0, 46
	s_nop 1
	v_writelane_b32 v221, s1, 47
	s_add_u32 s0, s70, 0x2710000
	s_addc_u32 s1, s71, 0
	v_writelane_b32 v221, s0, 48
	s_lshl_b32 s42, s41, 3
	s_nop 0
	v_writelane_b32 v221, s1, 49
	s_lshl_b32 s0, s6, 3
	s_cmp_lt_i32 s27, s0
	v_writelane_b32 v221, s0, 50
	s_cselect_b64 s[0:1], -1, 0
	v_writelane_b32 v221, s0, 51
	s_nop 1
	v_writelane_b32 v221, s1, 52
	s_add_u32 s0, s70, 0x5872400
	s_addc_u32 s1, s71, 0
	v_writelane_b32 v221, s0, 53
	s_nop 1
	v_writelane_b32 v221, s1, 54
	s_and_b64 s[0:1], s[14:15], exec
	s_mov_b64 s[0:1], 0x1400
	s_cselect_b32 s8, s10, s72
	v_lshl_add_u64 v[110:111], v[0:1], 0, s[0:1]
	s_mov_b64 s[0:1], 0x2400
	s_cselect_b32 s9, s11, s73
	v_lshl_add_u64 v[112:113], v[0:1], 0, s[0:1]
	s_cselect_b32 s0, s75, s74
	s_add_u32 s10, s8, 0x200
	s_addc_u32 s11, s9, 0
	v_writelane_b32 v221, s10, 55
	s_nop 1
	v_writelane_b32 v221, s11, 56
	s_add_u32 s10, s8, 0x1000
	s_addc_u32 s11, s9, 0
	v_writelane_b32 v221, s10, 57
	s_nop 1
	v_writelane_b32 v221, s11, 58
	s_add_u32 s10, s8, 0x1100
	s_addc_u32 s11, s9, 0
	v_writelane_b32 v221, s10, 59
	s_nop 1
	v_writelane_b32 v221, s11, 60
	s_add_u32 s10, s8, 0x1200
	s_addc_u32 s11, s9, 0
	v_writelane_b32 v221, s10, 61
	s_nop 1
	v_writelane_b32 v221, s11, 62
	s_add_u32 s10, s8, 0x1300
	s_addc_u32 s11, s9, 0
	v_writelane_b32 v221, s10, 63
	s_cmp_eq_u32 s0, 15
	s_nop 0
	v_writelane_b32 v220, s11, 0
	s_cselect_b64 s[10:11], -1, 0
	v_writelane_b32 v220, s10, 1
	s_cmp_eq_u32 s0, 14
	s_nop 0
	v_writelane_b32 v220, s11, 2
	s_cselect_b64 s[10:11], -1, 0
	v_writelane_b32 v220, s10, 3
	s_cmp_eq_u32 s0, 13
	s_nop 0
	v_writelane_b32 v220, s11, 4
	s_cselect_b64 s[10:11], -1, 0
	v_writelane_b32 v220, s10, 5
	s_cmp_eq_u32 s0, 12
	s_nop 0
	v_writelane_b32 v220, s11, 6
	s_cselect_b64 s[10:11], -1, 0
	v_writelane_b32 v220, s10, 7
	s_cmp_eq_u32 s0, 11
	s_nop 0
	v_writelane_b32 v220, s11, 8
	s_cselect_b64 s[10:11], -1, 0
	v_writelane_b32 v220, s10, 9
	s_cmp_eq_u32 s0, 10
	s_nop 0
	v_writelane_b32 v220, s11, 10
	s_cselect_b64 s[10:11], -1, 0
	v_writelane_b32 v220, s10, 11
	s_cmp_eq_u32 s0, 9
	s_nop 0
	v_writelane_b32 v220, s11, 12
	s_cselect_b64 s[10:11], -1, 0
	v_writelane_b32 v220, s10, 13
	s_cmp_eq_u32 s0, 8
	s_nop 0
	v_writelane_b32 v220, s11, 14
	s_cselect_b64 s[10:11], -1, 0
	v_writelane_b32 v220, s10, 15
	s_cmp_eq_u32 s0, 7
	s_nop 0
	v_writelane_b32 v220, s11, 16
	s_cselect_b64 s[10:11], -1, 0
	v_writelane_b32 v220, s10, 17
	s_cmp_eq_u32 s0, 6
	s_nop 0
	v_writelane_b32 v220, s11, 18
	s_cselect_b64 s[10:11], -1, 0
	v_writelane_b32 v220, s10, 19
	s_cmp_eq_u32 s0, 5
	s_nop 0
	v_writelane_b32 v220, s11, 20
	s_cselect_b64 s[10:11], -1, 0
	v_writelane_b32 v220, s10, 21
	s_cmp_eq_u32 s0, 4
	s_nop 0
	v_writelane_b32 v220, s11, 22
	s_cselect_b64 s[10:11], -1, 0
	v_writelane_b32 v220, s10, 23
	s_cmp_eq_u32 s0, 3
	s_nop 0
	v_writelane_b32 v220, s11, 24
	s_cselect_b64 s[10:11], -1, 0
	v_writelane_b32 v220, s10, 25
	s_cmp_eq_u32 s0, 2
	s_nop 0
	v_writelane_b32 v220, s11, 26
	s_cselect_b64 s[10:11], -1, 0
	v_writelane_b32 v220, s10, 27
	s_cmp_eq_u32 s0, 1
	s_nop 0
	v_writelane_b32 v220, s11, 28
	s_cselect_b64 s[10:11], -1, 0
	v_writelane_b32 v220, s10, 29
	s_cmp_eq_u32 s0, 0
	s_nop 0
	v_writelane_b32 v220, s11, 30
	s_cselect_b64 s[10:11], -1, 0
	s_lshl_b32 s0, s0, 8
	s_add_u32 s0, s8, s0
	v_writelane_b32 v220, s10, 31
	s_addc_u32 s1, s9, 0
	s_nop 0
	v_writelane_b32 v220, s11, 32
	s_add_u32 s10, s0, 0x1400
	s_addc_u32 s11, s1, 0
	v_writelane_b32 v220, s10, 33
	s_add_u32 s0, s0, 0x2400
	s_addc_u32 s1, s1, 0
	v_writelane_b32 v220, s11, 34
	v_writelane_b32 v220, s0, 35
	s_nop 1
	v_writelane_b32 v220, s1, 36
	s_add_u32 s0, s8, 0x3400
	s_addc_u32 s1, s9, 0
	v_writelane_b32 v220, s0, 37
	s_nop 1
	v_writelane_b32 v220, s1, 38
	s_add_u32 s0, s8, 0x3500
	v_writelane_b32 v220, s8, 39
	s_addc_u32 s1, s9, 0
	s_lshl_b32 s44, s24, 2
	v_writelane_b32 v220, s9, 40
	s_lshl_b32 s46, s25, 2
	v_writelane_b32 v220, s0, 41
	s_cmpk_lt_i32 s24, 0x480
	v_readlane_b32 s8, v223, 6
	v_writelane_b32 v220, s1, 42
	s_cselect_b64 s[0:1], -1, 0
	v_writelane_b32 v220, s0, 43
	s_cmpk_lt_i32 s24, 0x940
	v_readlane_b32 s18, v223, 16
	v_writelane_b32 v220, s1, 44
	s_cselect_b64 s[0:1], -1, 0
	v_readlane_b32 s19, v223, 17
	v_writelane_b32 v220, s0, 45
	s_cmp_lg_u64 s[18:19], 0
	v_readlane_b32 s14, v223, 12
	v_writelane_b32 v220, s1, 46
	v_readlane_b32 s15, v223, 13
	s_cselect_b64 s[0:1], -1, 0
	v_writelane_b32 v220, s0, 47
	s_cmp_lg_u64 s[14:15], 0
	v_readlane_b32 s9, v223, 7
	v_writelane_b32 v220, s1, 48
	s_cselect_b64 s[0:1], -1, 0
	v_writelane_b32 v220, s0, 49
	s_cmpk_lt_i32 s24, 0xaa0
	v_readlane_b32 s10, v223, 8
	v_writelane_b32 v220, s1, 50
	s_cselect_b64 s[0:1], -1, 0
	v_writelane_b32 v220, s0, 51
	v_readlane_b32 s11, v223, 9
	v_readlane_b32 s12, v223, 10
	v_writelane_b32 v220, s1, 52
	s_add_i32 s0, s34, -1
	v_writelane_b32 v220, s0, 53
	s_add_u32 s0, s70, 0xb00000
	s_addc_u32 s1, s71, 0
	v_writelane_b32 v220, s0, 54
	v_readlane_b32 s13, v223, 11
	v_readlane_b32 s20, v223, 18
	v_writelane_b32 v220, s1, 55
	s_add_u32 s0, s70, 0x1b80000
	s_addc_u32 s1, s71, 0
	v_writelane_b32 v220, s0, 56
	v_readlane_b32 s21, v223, 19
	v_readlane_b32 s22, v223, 20
	v_writelane_b32 v220, s1, 57
	v_writelane_b32 v220, s31, 58
	s_lshl_b32 s0, s31, 7
	v_writelane_b32 v220, s0, 59
	v_writelane_b32 v220, s30, 60
	s_lshl_b32 s0, s30, 7
	v_writelane_b32 v220, s0, 61
	s_add_u32 s0, s70, 0xf172080
	s_addc_u32 s1, s71, 0
	v_writelane_b32 v220, s0, 62
; template <int EPI, int MI>
; DI void gemm_phase(const GemmDesc& g, char* smem, int vb, int nvb) {
;   const bool xm = (nvb & 7) == 0 && (g.nM & 7) == 0;
;   const int xcd = vb & 7;
;   const int mPer = xm ? (g.nM >> 3) : g.nM;
;   const int PM = (mPer % 9 == 0) ? 9 : ((mPer & 7) == 0 ? 8 : ((mPer % 6) == 0 ? 6 : mPer));
;   const int per = PM * g.nN;
;   const int local = mPer * g.nN;
;   const int start = xm ? (vb >> 3) : vb, step = xm ? (nvb >> 3) : nvb;
;   const int mbase = xm ? xcd * mPer : 0;
;   for (int q = start; q < local; q += step) {
;     const int mg = q / per;
;     const int rem = q - mg * per;
;     const int tn = rem / PM;
;     const int tm = mbase + mg * PM + (rem - tn * PM);
;     gemm_tile<EPI, MI>(g, tm, tn, smem);
;   }
	v_readlane_b32 s23, v223, 21
	s_mov_b32 s9, 0x800000
	v_writelane_b32 v220, s1, 63
	s_add_u32 s0, s70, 0xf172100
	s_addc_u32 s1, s71, 0
	v_writelane_b32 v219, s0, 0
	s_mov_b32 s11, 0x3f317217
	s_mov_b32 s22, 0xff800000
	v_writelane_b32 v219, s1, 1
	s_add_u32 s0, s70, 0xf172180
	s_addc_u32 s1, s71, 0
	v_writelane_b32 v219, s0, 2
	s_mov_b32 s23, 0x66666667
	s_mov_b32 s20, 0
	v_writelane_b32 v219, s1, 3
	s_add_u32 s0, s70, 0xf172200
	s_addc_u32 s1, s71, 0
	v_writelane_b32 v219, s0, 4
	s_mov_b32 s21, 0
	s_mov_b64 s[30:31], 0x34c2080
	v_writelane_b32 v219, s1, 5
	s_add_u32 s0, s70, 0xf172280
	s_addc_u32 s1, s71, 0
	v_writelane_b32 v219, s0, 6
	s_mov_b64 s[12:13], 0x100
	v_readlane_b32 s16, v223, 14
	v_writelane_b32 v219, s1, 7
	s_add_u32 s0, s70, 0xf172300
	s_addc_u32 s1, s71, 0
	v_writelane_b32 v219, s0, 8
	v_readlane_b32 s17, v223, 15
	s_nop 0
	v_writelane_b32 v219, s1, 9
	s_add_u32 s0, s70, 0xf172380
	s_addc_u32 s1, s71, 0
	v_writelane_b32 v219, s0, 10
	s_nop 1
	v_writelane_b32 v219, s1, 11
	s_add_u32 s0, s70, 0xbb720c0
	s_addc_u32 s1, s71, 0
	v_writelane_b32 v219, s0, 12
	s_nop 1
	v_writelane_b32 v219, s1, 13
	s_add_u32 s0, s70, 0xbb72180
	s_addc_u32 s1, s71, 0
	v_writelane_b32 v219, s0, 14
	s_nop 1
	v_writelane_b32 v219, s1, 15
	s_add_u32 s0, s70, 0xbb72240
	s_addc_u32 s1, s71, 0
	v_writelane_b32 v219, s0, 16
	s_nop 1
	v_writelane_b32 v219, s1, 17
	s_add_u32 s0, s70, 0xbb72300
	s_addc_u32 s1, s71, 0
	v_writelane_b32 v219, s0, 18
	s_nop 1
	v_writelane_b32 v219, s1, 19
	s_add_u32 s0, s70, 0xbb723c0
	s_addc_u32 s1, s71, 0
	v_writelane_b32 v219, s0, 20
	s_nop 1
	v_writelane_b32 v219, s1, 21
	s_add_u32 s0, s70, 0xbb72480
	s_addc_u32 s1, s71, 0
	v_writelane_b32 v219, s0, 22
	s_nop 1
	v_writelane_b32 v219, s1, 23
	s_add_u32 s0, s70, 0x3472080
	s_addc_u32 s1, s71, 0
	v_writelane_b32 v219, s0, 24
	s_nop 1
	v_writelane_b32 v219, s1, 25
	s_add_u32 s0, s70, 0x3472100
	s_addc_u32 s1, s71, 0
	v_writelane_b32 v219, s0, 26
	s_nop 1
	v_writelane_b32 v219, s1, 27
	s_add_u32 s0, s70, 0x3472180
	s_addc_u32 s1, s71, 0
	v_writelane_b32 v219, s0, 28
	s_nop 1
	v_writelane_b32 v219, s1, 29
	s_add_u32 s0, s70, 0x3472200
	s_addc_u32 s1, s71, 0
	v_writelane_b32 v219, s0, 30
	s_nop 1
	v_writelane_b32 v219, s1, 31
	s_add_u32 s0, s70, 0x3472280
	s_addc_u32 s1, s71, 0
	v_writelane_b32 v219, s0, 32
	s_nop 1
	v_writelane_b32 v219, s1, 33
	s_add_u32 s0, s70, 0x3472300
	s_addc_u32 s1, s71, 0
	v_writelane_b32 v219, s0, 34
	s_nop 1
	v_writelane_b32 v219, s1, 35
	s_add_u32 s0, s70, 0x3472380
	s_addc_u32 s1, s71, 0
	v_writelane_b32 v219, s0, 36
	s_nop 1
	v_writelane_b32 v219, s1, 37
	s_add_u32 s0, s70, 0xbb72540
	s_addc_u32 s1, s71, 0
	s_abs_i32 s8, s34
	v_cvt_f32_u32_e32 v0, s8
	v_writelane_b32 v219, s0, 38
	v_rcp_iflag_f32_e32 v0, v0
	s_nop 0
	v_writelane_b32 v219, s1, 39
	s_sub_i32 s0, 0, s8
	v_mul_f32_e32 v0, 0x4f7ffffe, v0
	v_cvt_u32_f32_e32 v0, v0
	s_nop 0
	v_readfirstlane_b32 s1, v0
	s_mul_i32 s0, s0, s1
	s_mul_hi_u32 s0, s1, s0
	s_add_i32 s1, s1, s0
	s_sub_i32 s0, 0xffffb801, s34
	s_max_i32 s0, s5, s0
	v_writelane_b32 v219, s1, 40
	s_mul_hi_u32 s1, s0, s1
	s_mul_i32 s2, s1, s8
	s_sub_i32 s0, s0, s2
	s_ashr_i32 s2, s5, 31
	s_bfe_i32 s5, s43, 0x1001d
	v_writelane_b32 v219, s5, 41
	s_xor_b32 s2, s2, s5
	s_add_i32 s5, s1, 1
	s_sub_i32 s6, s0, s8
	s_cmp_ge_u32 s0, s8
	s_cselect_b32 s1, s5, s1
	s_cselect_b32 s0, s6, s0
	s_add_i32 s5, s1, 1
	s_cmp_ge_u32 s0, s8
	s_cselect_b32 s0, s5, s1
	s_xor_b32 s0, s0, s2
	v_writelane_b32 v219, s8, 42
	s_sub_i32 s0, s0, s2
	v_writelane_b32 v219, s0, 43
	s_mul_i32 s0, s40, 44
	v_cvt_f32_u32_e32 v0, s0
	v_writelane_b32 v219, s0, 44
	s_sub_i32 s0, 0, s0
	s_mul_hi_i32 s5, s34, 0x1580
	v_rcp_iflag_f32_e32 v0, v0
	s_movk_i32 s6, 0x60
	s_movk_i32 s8, 0x4000
	s_mov_b32 s2, 0x358637bd
	v_mul_f32_e32 v0, 0x4f7ffffe, v0
	v_cvt_u32_f32_e32 v0, v0
	s_nop 0
	v_readfirstlane_b32 s1, v0
	v_cvt_f32_ubyte0_e32 v0, s40
	v_rcp_iflag_f32_e32 v0, v0
	s_mul_i32 s0, s0, s1
	s_mul_hi_u32 s0, s1, s0
	s_add_i32 s0, s1, s0
	v_mul_f32_e32 v0, 0x4f7ffffe, v0
	v_cvt_u32_f32_e32 v0, v0
	v_writelane_b32 v219, s0, 45
	s_sub_i32 s0, 0, s40
	v_readfirstlane_b32 s1, v0
	v_cvt_f32_ubyte0_e32 v0, s35
	v_rcp_iflag_f32_e32 v0, v0
	s_mul_i32 s0, s0, s1
	s_mul_hi_u32 s0, s1, s0
	s_add_i32 s0, s1, s0
	v_mul_f32_e32 v0, 0x4f7ffffe, v0
	v_cvt_u32_f32_e32 v0, v0
	v_writelane_b32 v219, s0, 46
	s_sub_i32 s0, 0, s35
	v_writelane_b32 v219, s35, 47
	v_readfirstlane_b32 s1, v0
	v_cvt_f32_ubyte0_e32 v0, s7
; template <int EPI, int MI>
; DI void gemm_phase(const GemmDesc& g, char* smem, int vb, int nvb) {
;   const bool xm = (nvb & 7) == 0 && (g.nM & 7) == 0;
;   const int xcd = vb & 7;
;   const int mPer = xm ? (g.nM >> 3) : g.nM;
;   const int PM = (mPer % 9 == 0) ? 9 : ((mPer & 7) == 0 ? 8 : ((mPer % 6) == 0 ? 6 : mPer));
;   const int per = PM * g.nN;
;   const int local = mPer * g.nN;
;   const int start = xm ? (vb >> 3) : vb, step = xm ? (nvb >> 3) : nvb;
;   const int mbase = xm ? xcd * mPer : 0;
;   for (int q = start; q < local; q += step) {
;     const int mg = q / per;
;     const int rem = q - mg * per;
;     const int tn = rem / PM;
;     const int tm = mbase + mg * PM + (rem - tn * PM);
;     gemm_tile<EPI, MI>(g, tm, tn, smem);
;   }
	v_rcp_iflag_f32_e32 v0, v0
	s_mul_i32 s0, s0, s1
	s_mul_hi_u32 s0, s1, s0
	s_add_i32 s0, s1, s0
	v_mul_f32_e32 v0, 0x4f7ffffe, v0
	v_cvt_u32_f32_e32 v0, v0
	v_writelane_b32 v219, s0, 48
	s_sub_i32 s0, 0, s7
	v_writelane_b32 v219, s7, 49
	v_readfirstlane_b32 s1, v0
	v_cvt_f32_ubyte0_e32 v0, s39
	v_rcp_iflag_f32_e32 v0, v0
	s_mul_i32 s0, s0, s1
	s_mul_hi_u32 s0, s1, s0
	s_add_i32 s0, s1, s0
	v_mul_f32_e32 v0, 0x4f7ffffe, v0
	v_cvt_u32_f32_e32 v0, v0
	v_writelane_b32 v219, s0, 50
	s_sub_i32 s0, 0, s39
	v_writelane_b32 v219, s39, 51
	v_readfirstlane_b32 s1, v0
	s_mul_i32 s0, s0, s1
	s_mul_hi_u32 s0, s1, s0
	s_add_i32 s0, s1, s0
	v_writelane_b32 v219, s0, 52
	s_mul_i32 s0, s41, 6
	v_cvt_f32_ubyte0_e32 v0, s0
	v_rcp_iflag_f32_e32 v0, v0
	v_writelane_b32 v219, s0, 53
	s_sub_i32 s0, 0, s0
	s_ashr_i32 s35, s34, 31
	v_mul_f32_e32 v0, 0x4f7ffffe, v0
	v_cvt_u32_f32_e32 v0, v0
	s_ashr_i32 s39, s38, 31
	s_movk_i32 s7, 0x1580
	v_readfirstlane_b32 s1, v0
	v_cvt_f32_ubyte0_e32 v0, s41
	v_rcp_iflag_f32_e32 v0, v0
	s_mul_i32 s0, s0, s1
	s_mul_hi_u32 s0, s1, s0
	s_add_i32 s0, s1, s0
	v_mul_f32_e32 v0, 0x4f7ffffe, v0
	v_cvt_u32_f32_e32 v0, v0
	v_writelane_b32 v219, s0, 54
	s_sub_i32 s0, 0, s41
	v_readfirstlane_b32 s1, v0
	v_cvt_f32_ubyte0_e32 v0, s42
	v_rcp_iflag_f32_e32 v0, v0
	s_mul_i32 s0, s0, s1
	s_mul_hi_u32 s0, s1, s0
	s_add_i32 s0, s1, s0
	v_mul_f32_e32 v0, 0x4f7ffffe, v0
	v_cvt_u32_f32_e32 v0, v0
	v_writelane_b32 v219, s0, 55
	v_writelane_b32 v219, s42, 56
	s_sub_i32 s1, 0, s42
	v_readfirstlane_b32 s0, v0
	v_writelane_b32 v219, s1, 57
	s_mul_i32 s1, s1, s0
	s_mul_hi_u32 s1, s0, s1
	s_add_i32 s0, s0, s1
	v_writelane_b32 v219, s0, 58
	s_add_i32 s0, s29, s54
	v_writelane_b32 v219, s29, 59
	s_mulk_i32 s0, 0xc0
	v_writelane_b32 v219, s0, 60
	s_mul_i32 s0, s43, 0x4900
	s_mul_hi_i32 s1, s34, 0x1240
	v_writelane_b32 v219, s0, 61
	s_nop 1
	v_writelane_b32 v219, s1, 62
	v_writelane_b32 v219, s38, 63
	s_lshl_b64 s[0:1], s[34:35], 7
	s_nop 0
	v_writelane_b32 v218, s39, 0
	v_writelane_b32 v218, s0, 1
	s_nop 1
	v_writelane_b32 v218, s1, 2
	s_lshl_b64 s[0:1], s[34:35], 8
	v_writelane_b32 v218, s0, 3
	s_nop 1
	v_writelane_b32 v218, s1, 4
	s_lshl_b64 s[0:1], s[34:35], 10
	v_writelane_b32 v218, s0, 5
	s_mov_b32 s35, 0x7f800000
	s_nop 0
	v_writelane_b32 v218, s1, 6
	s_add_u32 s0, s70, 0x5872848
	s_addc_u32 s1, s71, 0
	v_writelane_b32 v218, s0, 7
	s_ashr_i32 s45, s44, 31
	s_ashr_i32 s47, s46, 31
	v_writelane_b32 v218, s1, 8
	s_add_i32 s0, s27, s4
	s_mulk_i32 s0, 0xc0
	v_writelane_b32 v218, s27, 9
	s_addk_i32 s0, 0xb0
	v_writelane_b32 v218, s0, 10
	v_writelane_b32 v218, s44, 11
	s_mul_i32 s0, s25, 0x5600
	s_mul_hi_i32 s1, s46, 0x1580
	v_writelane_b32 v218, s45, 12
	v_writelane_b32 v218, s0, 13
	s_mul_i32 s4, s43, 0x5600
	s_nop 0
	v_writelane_b32 v218, s1, 14
	s_mul_i32 s0, s25, 0x1800
	s_mul_hi_i32 s1, s46, 0x600
	v_writelane_b32 v218, s0, 15
	s_nop 1
	v_writelane_b32 v218, s1, 16
	v_writelane_b32 v218, s24, 17
	s_lshl_b32 s0, s24, 4
	v_writelane_b32 v218, s0, 18
	v_writelane_b32 v218, s25, 19
	s_lshl_b32 s0, s25, 4
	v_writelane_b32 v218, s0, 20
	s_mov_b32 s0, s46
	v_writelane_b32 v218, s0, 21
	s_mov_b64 s[24:25], 0x3492080
	s_nop 0
	v_writelane_b32 v218, s1, 22
	s_lshl_b64 s[0:1], s[46:47], 11
	v_writelane_b32 v218, s0, 23
	s_nop 1
	v_writelane_b32 v218, s1, 24
	s_add_u32 s0, s70, 0x5873188
	s_addc_u32 s1, s71, 0
	v_writelane_b32 v218, s0, 25
	s_add_i32 s10, 0, 0x10000
	s_add_i32 s14, 0, 0xc020
	v_writelane_b32 v218, s1, 26
	s_mov_b32 s0, s34
	v_writelane_b32 v218, s0, 27
	s_mov_b32 s34, 0x3e000000
	s_nop 0
	v_writelane_b32 v218, s1, 28
	v_writelane_b32 v218, s4, 29
	s_mul_i32 s0, s28, 0xc0
	s_nop 0
	v_writelane_b32 v218, s5, 30
	v_writelane_b32 v218, s0, 31
	v_writelane_b32 v218, s40, 32
	s_mul_i32 s0, s40, 0xc0
	v_writelane_b32 v218, s0, 33
	v_writelane_b32 v218, s41, 34
	s_mul_i32 s0, s41, 0xc0
	v_writelane_b32 v218, s0, 35
	v_writelane_b32 v218, s26, 36
	s_mul_i32 s0, s26, 0xc0
	v_writelane_b32 v218, s0, 37
	v_writelane_b32 v218, s28, 38
	s_lshl_b32 s0, s28, 7
	v_writelane_b32 v218, s0, 39
	s_add_i32 s0, 0, 0xb400
	v_writelane_b32 v218, s0, 40
	s_add_i32 s0, 0, 0xc400
	v_writelane_b32 v218, s0, 41
	s_add_i32 s0, 0, 0x8100
	v_writelane_b32 v218, s0, 42
	v_writelane_b32 v218, s43, 43
	v_writelane_b32 v218, s54, 44
	s_mov_b64 s[40:41], -1
	s_mov_b64 s[26:27], 0x34a2080
	s_mov_b64 s[28:29], 0x34b2080
	v_writelane_b32 v218, s92, 45
	s_nop 1
	v_writelane_b32 v218, s93, 46
	s_branch .LBB0_131
